# attention K-tile loop tail de-serialised: next tile K/V LDS stores issued at start of the exp section (free stage) instead of right before the barrier; skip path unchanged; on top of v8
# speedup vs baseline: 1.0008x; 1.0008x over previous
; __device__ __forceinline__ unsigned pk2(float lo, float hi) { f32x2 v = {lo, hi}; return __builtin_bit_cast(unsigned, __builtin_convertvector(v, bf16v2)); }
; #define MFMA32(a, b, c) __builtin_amdgcn_mfma_f32_32x32x16_bf16((a), (b), (c), 0, 0, 0)
; #define TRV(p) trv_read((const LAS unsigned char*)(p))
; #define ATT_LSTORE(st) do { _Pragma("unroll") for (int i = 0; i < 3; ++i) *(LAS u32x4*)(lds + (st) * STG_B + klo + 128 * i) = kr[i]; \
;         _Pragma("unroll") for (int i = 0; i < 2; ++i) *(LAS u32x4*)(lds + (st) * STG_B + vlo + 32 * i * VROW_B) = vr[i]; } while (0)
; DI void attn_block(const bf16_t* Q, const bf16_t* Kb, const bf16_t* Vt, bf16_t* AO, LAS unsigned char* lds, int bh, int qb, int tid, int wave, int lane) {
;     ...
;             float ls = 0.f;
; #pragma unroll
;             for (int kb = 0; kb < 2; ++kb)
; #pragma unroll
;                 for (int i = 0; i < 16; ++i) { const float p = __builtin_amdgcn_exp2f(sa[kb][i] - m); sa[kb][i] = p; ls += p; }
;             l += ls;
;             bf16x8 pf[4];
; #pragma unroll
;             for (int kb = 0; kb < 2; ++kb)
; #pragma unroll
;                 for (int s = 0; s < 2; ++s) { u32x4 w; w.x = pk2(sa[kb][8 * s], sa[kb][8 * s + 1]); w.y = pk2(sa[kb][8 * s + 2], sa[kb][8 * s + 3]);
;                     w.z = pk2(sa[kb][8 * s + 4], sa[kb][8 * s + 5]); w.w = pk2(sa[kb][8 * s + 6], sa[kb][8 * s + 7]); pf[kb * 2 + s] = __builtin_bit_cast(bf16x8, w); }
;             {
;                 bf16x8 fv[2][4];
; #pragma unroll
;                 for (int j = 0; j < 4; ++j) fv[0][j] = TRV(sb + voff + j * 16 * VROW_B);
;                 __builtin_amdgcn_sched_barrier(0);
; #pragma unroll
;                 for (int d = 0; d < 4; ++d) {
;                     if (d < 3) {
; #pragma unroll
;                         for (int j = 0; j < 4; ++j) fv[(d + 1) & 1][j] = TRV(sb + voff + (d + 1) * 64 + j * 16 * VROW_B);
;                     }
; #pragma unroll
;                     for (int j = 0; j < 4; ++j) o[d] = MFMA32(fv[d & 1][j], pf[j], o[d]);
;                     __builtin_amdgcn_sched_barrier(0);
;                 }
;             }
;         }
;         if (more) ATT_LSTORE(st ^ 1);
.LBB0_423:
	v_add_u32_e32 v228, 0xb400, v197
	v_add_u32_e32 v229, 0xb400, v198
	v_subrev_u32_e32 v228, s34, v228
	v_subrev_u32_e32 v229, s34, v229
	s_waitcnt vmcnt(0)
	ds_write_b128 v228, v[2:5]
	ds_write_b128 v228, v[6:9] offset:128
	ds_write_b128 v228, v[10:13] offset:256
	ds_write_b128 v229, v[160:163] offset:25600
	ds_write_b128 v229, v[164:167] offset:35840
	v_sub_f32_e32 v80, v80, v205
	v_exp_f32_e32 v80, v80
	v_sub_f32_e32 v81, v81, v205
	v_exp_f32_e32 v81, v81
	v_sub_f32_e32 v82, v82, v205
	v_exp_f32_e32 v82, v82
	v_sub_f32_e32 v83, v83, v205
	v_exp_f32_e32 v83, v83
	v_sub_f32_e32 v84, v84, v205
	v_add_f32_e32 v206, 0, v80
	v_exp_f32_e32 v84, v84
	v_sub_f32_e32 v85, v85, v205
	v_add_f32_e32 v206, v81, v206
	v_exp_f32_e32 v85, v85
	v_sub_f32_e32 v86, v86, v205
	v_add_f32_e32 v206, v82, v206
	v_exp_f32_e32 v86, v86
	v_sub_f32_e32 v87, v87, v205
	v_add_f32_e32 v206, v83, v206
	v_exp_f32_e32 v87, v87
	v_sub_f32_e32 v88, v88, v205
	v_add_f32_e32 v206, v84, v206
	v_exp_f32_e32 v88, v88
	v_sub_f32_e32 v89, v89, v205
	v_add_f32_e32 v206, v85, v206
	v_exp_f32_e32 v89, v89
	v_sub_f32_e32 v90, v90, v205
	v_add_f32_e32 v206, v86, v206
	v_exp_f32_e32 v90, v90
	v_sub_f32_e32 v91, v91, v205
	v_add_f32_e32 v206, v87, v206
	v_exp_f32_e32 v91, v91
	v_sub_f32_e32 v92, v92, v205
	v_add_f32_e32 v206, v88, v206
	v_exp_f32_e32 v92, v92
	v_sub_f32_e32 v93, v93, v205
	v_add_f32_e32 v206, v89, v206
	v_exp_f32_e32 v93, v93
	v_sub_f32_e32 v94, v94, v205
	v_add_f32_e32 v206, v90, v206
	v_exp_f32_e32 v94, v94
	v_sub_f32_e32 v95, v95, v205
	v_add_f32_e32 v206, v91, v206
	v_exp_f32_e32 v95, v95
	v_sub_f32_e32 v96, v96, v205
	v_sub_f32_e32 v97, v97, v205
	v_add_f32_e32 v206, v92, v206
	v_exp_f32_e32 v96, v96
	v_exp_f32_e32 v97, v97
	v_add_f32_e32 v206, v93, v206
	v_sub_f32_e32 v98, v98, v205
	v_add_f32_e32 v206, v94, v206
	v_exp_f32_e32 v98, v98
	v_sub_f32_e32 v99, v99, v205
	v_add_f32_e32 v206, v95, v206
	v_exp_f32_e32 v99, v99
	v_sub_f32_e32 v100, v100, v205
	v_exp_f32_e32 v100, v100
	v_sub_f32_e32 v101, v101, v205
	v_cvt_pk_bf16_f32 v80, v80, v81
	v_cvt_pk_bf16_f32 v81, v82, v83
	v_cvt_pk_bf16_f32 v82, v84, v85
	v_cvt_pk_bf16_f32 v84, v88, v89
	v_cvt_pk_bf16_f32 v88, v96, v97
	v_add_f32_e32 v96, v96, v206
	v_exp_f32_e32 v101, v101
	v_sub_f32_e32 v102, v102, v205
	v_add_f32_e32 v96, v97, v96
	v_exp_f32_e32 v102, v102
	v_sub_f32_e32 v103, v103, v205
	v_add_f32_e32 v96, v98, v96
	v_exp_f32_e32 v103, v103
	v_sub_f32_e32 v104, v104, v205
	v_add_f32_e32 v96, v99, v96
	v_exp_f32_e32 v104, v104
	v_sub_f32_e32 v105, v105, v205
	v_add_f32_e32 v96, v100, v96
	v_exp_f32_e32 v105, v105
	v_sub_f32_e32 v106, v106, v205
	v_add_f32_e32 v96, v101, v96
	v_exp_f32_e32 v106, v106
	v_sub_f32_e32 v107, v107, v205
	v_add_f32_e32 v96, v102, v96
	v_exp_f32_e32 v107, v107
	v_sub_f32_e32 v108, v108, v205
	v_add_f32_e32 v96, v103, v96
	v_exp_f32_e32 v207, v108
	v_sub_f32_e32 v108, v109, v205
	v_add_f32_e32 v96, v104, v96
	v_exp_f32_e32 v208, v108
	v_sub_f32_e32 v108, v110, v205
	v_add_f32_e32 v96, v105, v96
	v_exp_f32_e32 v209, v108
	v_sub_f32_e32 v108, v111, v205
	v_add_f32_e32 v96, v106, v96
	v_add_u32_e32 v211, s34, v201
	v_exp_f32_e32 v210, v108
	v_cvt_pk_bf16_f32 v83, v86, v87
	v_cvt_pk_bf16_f32 v85, v90, v91
	v_cvt_pk_bf16_f32 v86, v92, v93
	v_cvt_pk_bf16_f32 v89, v98, v99
	v_cvt_pk_bf16_f32 v90, v100, v101
	v_cvt_pk_bf16_f32 v91, v102, v103
	v_cvt_pk_bf16_f32 v92, v104, v105
	v_cvt_pk_bf16_f32 v93, v106, v107
	v_add_f32_e32 v206, v107, v96
	ds_read_b64_tr_b16 v[98:99], v211 offset:33280
	ds_read_b64_tr_b16 v[100:101], v211 offset:35840
	ds_read_b64_tr_b16 v[102:103], v211 offset:38400
	ds_read_b64_tr_b16 v[104:105], v211 offset:40960
	ds_read_b64_tr_b16 v[108:109], v211 offset:25600
	ds_read_b64_tr_b16 v[110:111], v211 offset:28160
	ds_read_b64_tr_b16 v[96:97], v211 offset:30720
	ds_read_b64_tr_b16 v[106:107], v211 offset:43520
	v_add_f32_e32 v206, v207, v206
	v_add_f32_e32 v206, v208, v206
	v_add_f32_e32 v206, v209, v206
	v_cvt_pk_bf16_f32 v87, v94, v95
	v_cvt_pk_bf16_f32 v94, v207, v208
	v_cvt_pk_bf16_f32 v95, v209, v210
	v_add_f32_e32 v210, v210, v206
	s_waitcnt lgkmcnt(2)
	v_mfma_f32_32x32x16_bf16 v[64:79], v[108:111], v[80:83], v[64:79]
	s_waitcnt lgkmcnt(1)
	v_mfma_f32_32x32x16_bf16 v[64:79], v[96:99], v[84:87], v[64:79]
	v_mfma_f32_32x32x16_bf16 v[64:79], v[100:103], v[88:91], v[64:79]
	ds_read_b64_tr_b16 v[98:99], v211 offset:33344
	ds_read_b64_tr_b16 v[100:101], v211 offset:35904
	ds_read_b64_tr_b16 v[102:103], v211 offset:38464
	ds_read_b64_tr_b16 v[108:109], v211 offset:41024
	ds_read_b64_tr_b16 v[206:207], v211 offset:25664
	ds_read_b64_tr_b16 v[208:209], v211 offset:28224
	ds_read_b64_tr_b16 v[96:97], v211 offset:30784
	ds_read_b64_tr_b16 v[110:111], v211 offset:43584
	s_waitcnt lgkmcnt(8)
	v_mfma_f32_32x32x16_bf16 v[64:79], v[104:107], v[92:95], v[64:79]
	s_waitcnt lgkmcnt(2)
	v_mfma_f32_32x32x16_bf16 v[48:63], v[206:209], v[80:83], v[48:63]
	s_waitcnt lgkmcnt(1)
	v_mfma_f32_32x32x16_bf16 v[48:63], v[96:99], v[84:87], v[48:63]
	v_mfma_f32_32x32x16_bf16 v[48:63], v[100:103], v[88:91], v[48:63]
	ds_read_b64_tr_b16 v[98:99], v211 offset:33408
	ds_read_b64_tr_b16 v[100:101], v211 offset:35968
	ds_read_b64_tr_b16 v[102:103], v211 offset:38528
	ds_read_b64_tr_b16 v[104:105], v211 offset:41088
	ds_read_b64_tr_b16 v[206:207], v211 offset:25728
	ds_read_b64_tr_b16 v[208:209], v211 offset:28288
	ds_read_b64_tr_b16 v[96:97], v211 offset:30848
	ds_read_b64_tr_b16 v[106:107], v211 offset:43648
	s_waitcnt lgkmcnt(8)
	v_mfma_f32_32x32x16_bf16 v[48:63], v[108:111], v[92:95], v[48:63]
	s_waitcnt lgkmcnt(2)
	v_mfma_f32_32x32x16_bf16 v[32:47], v[206:209], v[80:83], v[32:47]
	s_waitcnt lgkmcnt(1)
	v_mfma_f32_32x32x16_bf16 v[32:47], v[96:99], v[84:87], v[32:47]
	v_mfma_f32_32x32x16_bf16 v[32:47], v[100:103], v[88:91], v[32:47]
	ds_read_b64_tr_b16 v[98:99], v211 offset:33472
	ds_read_b64_tr_b16 v[100:101], v211 offset:36032
	ds_read_b64_tr_b16 v[102:103], v211 offset:38592
	ds_read_b64_tr_b16 v[108:109], v211 offset:41152
	ds_read_b64_tr_b16 v[206:207], v211 offset:25792
	ds_read_b64_tr_b16 v[208:209], v211 offset:28352
	ds_read_b64_tr_b16 v[96:97], v211 offset:30912
	ds_read_b64_tr_b16 v[110:111], v211 offset:43712
	s_waitcnt lgkmcnt(8)
	v_mfma_f32_32x32x16_bf16 v[32:47], v[104:107], v[92:95], v[32:47]
	s_waitcnt lgkmcnt(2)
	v_mfma_f32_32x32x16_bf16 v[16:31], v[206:209], v[80:83], v[16:31]
	s_waitcnt lgkmcnt(1)
	v_mfma_f32_32x32x16_bf16 v[16:31], v[96:99], v[84:87], v[16:31]
	v_mfma_f32_32x32x16_bf16 v[16:31], v[100:103], v[88:91], v[16:31]
	s_waitcnt lgkmcnt(0)
	v_mfma_f32_32x32x16_bf16 v[16:31], v[108:111], v[92:95], v[16:31]
	v_add_f32_e32 v204, v204, v210
	s_branch .Latt_tail_0
; #define ATT_LSTORE(st) do { _Pragma("unroll") for (int i = 0; i < 3; ++i) *(LAS u32x4*)(lds + (st) * STG_B + klo + 128 * i) = kr[i]; \
;         _Pragma("unroll") for (int i = 0; i < 2; ++i) *(LAS u32x4*)(lds + (st) * STG_B + vlo + 32 * i * VROW_B) = vr[i]; } while (0)
; DI void attn_block(const bf16_t* Q, const bf16_t* Kb, const bf16_t* Vt, bf16_t* AO, LAS unsigned char* lds, int bh, int qb, int tid, int wave, int lane) {
;     ...
;         if (more) ATT_LSTORE(st ^ 1);
;         __syncthreads();
.LBB0_424:
	s_xor_b32 s15, s15, 1
	s_mul_i32 s15, s15, 0xb400
	v_add_u32_e32 v80, s15, v197
	s_waitcnt vmcnt(4)
	ds_write_b128 v80, v[2:5]
	s_waitcnt vmcnt(3)
	ds_write_b128 v80, v[6:9] offset:128
	s_waitcnt vmcnt(2)
	ds_write_b128 v80, v[10:13] offset:256
	v_add_u32_e32 v2, s15, v198
	s_waitcnt vmcnt(1)
	ds_write_b128 v2, v[160:163] offset:25600
	s_waitcnt vmcnt(0)
	ds_write_b128 v2, v[164:167] offset:35840
.Latt_tail_0:
	s_add_i32 s4, s4, 64
	s_add_i32 s14, s14, 1
	v_lshl_add_u64 v[194:195], v[194:195], 0, s[10:11]
	s_cmp_eq_u32 s33, s4
	v_lshl_add_u64 v[192:193], v[192:193], 0, s[12:13]
	s_waitcnt lgkmcnt(0)
	s_barrier
	s_cbranch_scc1 .LBB0_430

; __device__ __forceinline__ unsigned pk2(float lo, float hi) { f32x2 v = {lo, hi}; return __builtin_bit_cast(unsigned, __builtin_convertvector(v, bf16v2)); }
; #define MFMA32(a, b, c) __builtin_amdgcn_mfma_f32_32x32x16_bf16((a), (b), (c), 0, 0, 0)
; #define TRV(p) trv_read((const LAS unsigned char*)(p))
; #define ATT_LSTORE(st) do { _Pragma("unroll") for (int i = 0; i < 3; ++i) *(LAS u32x4*)(lds + (st) * STG_B + klo + 128 * i) = kr[i]; \
;         _Pragma("unroll") for (int i = 0; i < 2; ++i) *(LAS u32x4*)(lds + (st) * STG_B + vlo + 32 * i * VROW_B) = vr[i]; } while (0)
; DI void attn_block(const bf16_t* Q, const bf16_t* Kb, const bf16_t* Vt, bf16_t* AO, LAS unsigned char* lds, int bh, int qb, int tid, int wave, int lane) {
;     ...
;             float ls = 0.f;
; #pragma unroll
;             for (int kb = 0; kb < 2; ++kb)
; #pragma unroll
;                 for (int i = 0; i < 16; ++i) { const float p = __builtin_amdgcn_exp2f(sa[kb][i] - m); sa[kb][i] = p; ls += p; }
;             l += ls;
;             bf16x8 pf[4];
; #pragma unroll
;             for (int kb = 0; kb < 2; ++kb)
; #pragma unroll
;                 for (int s = 0; s < 2; ++s) { u32x4 w; w.x = pk2(sa[kb][8 * s], sa[kb][8 * s + 1]); w.y = pk2(sa[kb][8 * s + 2], sa[kb][8 * s + 3]);
;                     w.z = pk2(sa[kb][8 * s + 4], sa[kb][8 * s + 5]); w.w = pk2(sa[kb][8 * s + 6], sa[kb][8 * s + 7]); pf[kb * 2 + s] = __builtin_bit_cast(bf16x8, w); }
;             {
;                 bf16x8 fv[2][4];
; #pragma unroll
;                 for (int j = 0; j < 4; ++j) fv[0][j] = TRV(sb + voff + j * 16 * VROW_B);
;                 __builtin_amdgcn_sched_barrier(0);
; #pragma unroll
;                 for (int d = 0; d < 4; ++d) {
;                     if (d < 3) {
; #pragma unroll
;                         for (int j = 0; j < 4; ++j) fv[(d + 1) & 1][j] = TRV(sb + voff + (d + 1) * 64 + j * 16 * VROW_B);
;                     }
; #pragma unroll
;                     for (int j = 0; j < 4; ++j) o[d] = MFMA32(fv[d & 1][j], pf[j], o[d]);
;                     __builtin_amdgcn_sched_barrier(0);
;                 }
;             }
;         }
;         if (more) ATT_LSTORE(st ^ 1);
.LBB0_437:
	v_add_u32_e32 v228, 0xb400, v197
	v_add_u32_e32 v229, 0xb400, v198
	v_subrev_u32_e32 v228, s30, v228
	v_subrev_u32_e32 v229, s30, v229
	s_waitcnt vmcnt(0)
	ds_write_b128 v228, v[2:5]
	ds_write_b128 v228, v[6:9] offset:128
	ds_write_b128 v228, v[10:13] offset:256
	ds_write_b128 v229, v[160:163] offset:25600
	ds_write_b128 v229, v[164:167] offset:35840
	v_sub_f32_e32 v1, v80, v189
	v_exp_f32_e32 v1, v1
	v_sub_f32_e32 v14, v81, v189
	v_exp_f32_e32 v14, v14
	v_sub_f32_e32 v15, v82, v189
	v_exp_f32_e32 v15, v15
	v_sub_f32_e32 v80, v83, v189
	v_exp_f32_e32 v81, v80
	v_sub_f32_e32 v82, v84, v189
	v_add_f32_e32 v80, 0, v1
	v_exp_f32_e32 v82, v82
	v_sub_f32_e32 v83, v85, v189
	v_add_f32_e32 v80, v14, v80
	v_exp_f32_e32 v83, v83
	v_sub_f32_e32 v84, v86, v189
	v_add_f32_e32 v80, v15, v80
	v_exp_f32_e32 v84, v84
	v_sub_f32_e32 v85, v87, v189
	v_add_f32_e32 v80, v81, v80
	v_exp_f32_e32 v85, v85
	v_sub_f32_e32 v86, v88, v189
	v_add_f32_e32 v80, v82, v80
	v_exp_f32_e32 v86, v86
	v_sub_f32_e32 v87, v89, v189
	v_add_f32_e32 v80, v83, v80
	v_exp_f32_e32 v87, v87
	v_sub_f32_e32 v88, v90, v189
	v_add_f32_e32 v80, v84, v80
	v_exp_f32_e32 v88, v88
	v_sub_f32_e32 v89, v91, v189
	v_add_f32_e32 v80, v85, v80
	v_exp_f32_e32 v89, v89
	v_sub_f32_e32 v90, v92, v189
	v_add_f32_e32 v80, v86, v80
	v_exp_f32_e32 v90, v90
	v_sub_f32_e32 v91, v93, v189
	v_add_f32_e32 v80, v87, v80
	v_exp_f32_e32 v91, v91
	v_sub_f32_e32 v92, v94, v189
	v_add_f32_e32 v80, v88, v80
	v_exp_f32_e32 v92, v92
	v_sub_f32_e32 v93, v95, v189
	v_add_f32_e32 v80, v89, v80
	v_exp_f32_e32 v93, v93
	v_add_f32_e32 v80, v90, v80
	v_add_f32_e32 v80, v91, v80
	v_add_f32_e32 v80, v92, v80
	v_add_f32_e32 v191, v93, v80
	v_sub_f32_e32 v80, v96, v189
	v_exp_f32_e32 v96, v80
	v_sub_f32_e32 v80, v97, v189
	v_exp_f32_e32 v97, v80
	v_sub_f32_e32 v80, v98, v189
	v_exp_f32_e32 v98, v80
	v_sub_f32_e32 v80, v99, v189
	v_exp_f32_e32 v99, v80
	v_sub_f32_e32 v80, v100, v189
	v_exp_f32_e32 v100, v80
	v_sub_f32_e32 v80, v101, v189
	v_exp_f32_e32 v101, v80
	v_sub_f32_e32 v80, v102, v189
	v_exp_f32_e32 v102, v80
	v_sub_f32_e32 v80, v103, v189
	v_exp_f32_e32 v103, v80
	v_sub_f32_e32 v80, v104, v189
	v_exp_f32_e32 v104, v80
	v_sub_f32_e32 v80, v105, v189
	v_exp_f32_e32 v105, v80
	v_sub_f32_e32 v80, v106, v189
	v_exp_f32_e32 v106, v80
	v_sub_f32_e32 v80, v107, v189
	v_exp_f32_e32 v107, v80
	v_sub_f32_e32 v80, v108, v189
	v_exp_f32_e32 v192, v80
	v_sub_f32_e32 v80, v109, v189
	v_exp_f32_e32 v193, v80
	v_sub_f32_e32 v80, v110, v189
	v_exp_f32_e32 v194, v80
	v_sub_f32_e32 v80, v111, v189
	v_exp_f32_e32 v195, v80
	v_cvt_pk_bf16_f32 v80, v1, v14
	v_add_f32_e32 v1, v96, v191
	v_add_f32_e32 v1, v97, v1
	v_add_f32_e32 v1, v98, v1
	v_add_f32_e32 v1, v99, v1
	v_add_f32_e32 v1, v100, v1
	v_add_f32_e32 v1, v101, v1
	v_add_f32_e32 v1, v102, v1
	v_add_f32_e32 v1, v103, v1
	v_add_f32_e32 v1, v104, v1
	v_add_f32_e32 v1, v105, v1
	v_add_f32_e32 v1, v106, v1
	v_add_u32_e32 v14, s30, v201
	v_cvt_pk_bf16_f32 v82, v82, v83
	v_cvt_pk_bf16_f32 v83, v84, v85
	v_cvt_pk_bf16_f32 v84, v86, v87
	v_cvt_pk_bf16_f32 v85, v88, v89
	v_cvt_pk_bf16_f32 v86, v90, v91
	v_cvt_pk_bf16_f32 v87, v92, v93
	v_cvt_pk_bf16_f32 v88, v96, v97
	v_cvt_pk_bf16_f32 v89, v98, v99
	v_cvt_pk_bf16_f32 v90, v100, v101
	v_cvt_pk_bf16_f32 v91, v102, v103
	v_cvt_pk_bf16_f32 v92, v104, v105
	v_cvt_pk_bf16_f32 v93, v106, v107
	v_add_f32_e32 v1, v107, v1
	ds_read_b64_tr_b16 v[98:99], v14 offset:33280
	ds_read_b64_tr_b16 v[100:101], v14 offset:35840
	ds_read_b64_tr_b16 v[102:103], v14 offset:38400
	ds_read_b64_tr_b16 v[104:105], v14 offset:40960
	ds_read_b64_tr_b16 v[108:109], v14 offset:25600
	ds_read_b64_tr_b16 v[110:111], v14 offset:28160
	ds_read_b64_tr_b16 v[96:97], v14 offset:30720
	ds_read_b64_tr_b16 v[106:107], v14 offset:43520
	v_add_f32_e32 v1, v192, v1
	v_add_f32_e32 v1, v193, v1
	v_add_f32_e32 v1, v194, v1
	v_cvt_pk_bf16_f32 v81, v15, v81
	v_cvt_pk_bf16_f32 v94, v192, v193
	v_cvt_pk_bf16_f32 v95, v194, v195
	v_add_f32_e32 v1, v195, v1
	s_waitcnt lgkmcnt(2)
	v_mfma_f32_32x32x16_bf16 v[64:79], v[108:111], v[80:83], v[64:79]
	s_waitcnt lgkmcnt(1)
	v_mfma_f32_32x32x16_bf16 v[64:79], v[96:99], v[84:87], v[64:79]
	v_mfma_f32_32x32x16_bf16 v[64:79], v[100:103], v[88:91], v[64:79]
	ds_read_b64_tr_b16 v[98:99], v14 offset:33344
	ds_read_b64_tr_b16 v[100:101], v14 offset:35904
	ds_read_b64_tr_b16 v[102:103], v14 offset:38464
	ds_read_b64_tr_b16 v[108:109], v14 offset:41024
	ds_read_b64_tr_b16 v[192:193], v14 offset:25664
	ds_read_b64_tr_b16 v[194:195], v14 offset:28224
	ds_read_b64_tr_b16 v[96:97], v14 offset:30784
	ds_read_b64_tr_b16 v[110:111], v14 offset:43584
	s_waitcnt lgkmcnt(8)
	v_mfma_f32_32x32x16_bf16 v[64:79], v[104:107], v[92:95], v[64:79]
	s_waitcnt lgkmcnt(2)
	v_mfma_f32_32x32x16_bf16 v[48:63], v[192:195], v[80:83], v[48:63]
	s_waitcnt lgkmcnt(1)
	v_mfma_f32_32x32x16_bf16 v[48:63], v[96:99], v[84:87], v[48:63]
	v_mfma_f32_32x32x16_bf16 v[48:63], v[100:103], v[88:91], v[48:63]
	ds_read_b64_tr_b16 v[98:99], v14 offset:33408
	ds_read_b64_tr_b16 v[100:101], v14 offset:35968
	ds_read_b64_tr_b16 v[102:103], v14 offset:38528
	ds_read_b64_tr_b16 v[104:105], v14 offset:41088
	ds_read_b64_tr_b16 v[192:193], v14 offset:25728
	ds_read_b64_tr_b16 v[194:195], v14 offset:28288
	ds_read_b64_tr_b16 v[96:97], v14 offset:30848
	ds_read_b64_tr_b16 v[106:107], v14 offset:43648
	s_waitcnt lgkmcnt(8)
	v_mfma_f32_32x32x16_bf16 v[48:63], v[108:111], v[92:95], v[48:63]
	s_waitcnt lgkmcnt(2)
	v_mfma_f32_32x32x16_bf16 v[32:47], v[192:195], v[80:83], v[32:47]
	s_waitcnt lgkmcnt(1)
	v_mfma_f32_32x32x16_bf16 v[32:47], v[96:99], v[84:87], v[32:47]
	v_mfma_f32_32x32x16_bf16 v[32:47], v[100:103], v[88:91], v[32:47]
	ds_read_b64_tr_b16 v[98:99], v14 offset:33472
	ds_read_b64_tr_b16 v[100:101], v14 offset:36032
	ds_read_b64_tr_b16 v[102:103], v14 offset:38592
	ds_read_b64_tr_b16 v[108:109], v14 offset:41152
	ds_read_b64_tr_b16 v[192:193], v14 offset:25792
	ds_read_b64_tr_b16 v[194:195], v14 offset:28352
	ds_read_b64_tr_b16 v[96:97], v14 offset:30912
	ds_read_b64_tr_b16 v[110:111], v14 offset:43712
	s_waitcnt lgkmcnt(8)
	v_mfma_f32_32x32x16_bf16 v[32:47], v[104:107], v[92:95], v[32:47]
	s_waitcnt lgkmcnt(2)
	v_mfma_f32_32x32x16_bf16 v[16:31], v[192:195], v[80:83], v[16:31]
	s_waitcnt lgkmcnt(1)
	v_mfma_f32_32x32x16_bf16 v[16:31], v[96:99], v[84:87], v[16:31]
	v_mfma_f32_32x32x16_bf16 v[16:31], v[100:103], v[88:91], v[16:31]
	s_waitcnt lgkmcnt(0)
	v_mfma_f32_32x32x16_bf16 v[16:31], v[108:111], v[92:95], v[16:31]
	v_add_f32_e32 v188, v188, v1
	s_branch .Latt_tail_1
; #define ATT_LSTORE(st) do { _Pragma("unroll") for (int i = 0; i < 3; ++i) *(LAS u32x4*)(lds + (st) * STG_B + klo + 128 * i) = kr[i]; \
;         _Pragma("unroll") for (int i = 0; i < 2; ++i) *(LAS u32x4*)(lds + (st) * STG_B + vlo + 32 * i * VROW_B) = vr[i]; } while (0)
; DI void attn_block(const bf16_t* Q, const bf16_t* Kb, const bf16_t* Vt, bf16_t* AO, LAS unsigned char* lds, int bh, int qb, int tid, int wave, int lane) {
;     ...
;         if (more) ATT_LSTORE(st ^ 1);
;         __syncthreads();
.LBB0_438:
	s_xor_b32 s29, s29, 1
	s_mul_i32 s29, s29, 0xb400
	v_add_u32_e32 v1, s29, v197
	s_waitcnt vmcnt(4)
	ds_write_b128 v1, v[2:5]
	s_waitcnt vmcnt(3)
	ds_write_b128 v1, v[6:9] offset:128
	s_waitcnt vmcnt(2)
	ds_write_b128 v1, v[10:13] offset:256
	v_add_u32_e32 v1, s29, v198
	s_waitcnt vmcnt(1)
	ds_write_b128 v1, v[160:163] offset:25600
	s_waitcnt vmcnt(0)
	ds_write_b128 v1, v[164:167] offset:35840
.Latt_tail_1:
	s_add_i32 s27, s27, 64
	s_add_i32 s28, s28, 1
	v_lshl_add_u64 v[184:185], v[184:185], 0, s[10:11]
	s_cmp_eq_u32 s15, s27
	v_lshl_add_u64 v[182:183], v[182:183], 0, s[12:13]
	s_waitcnt lgkmcnt(0)
	s_barrier
	s_cbranch_scc1 .LBB0_444
